# pair narrow stores into wide ones (2): even-mixer u/w block computed transposed, 8 global_store_dwordx2 instead of 32 global_store_short per thread and chunk
# baseline (speedup 1.0000x reference)
; __device__ __forceinline__ void phase_even_mix(const int wid_s, CParams& p, int j, LAS unsigned char* lds) {
;     ...
;             {
;                 const int mt = wave >> 1, nt0 = 2 * (wave & 1);
;                 f32x4 tacc[2];
; #pragma unroll
;                 for (int t = 0; t < 2; ++t) { const int jc = 16 * (nt0 + t) + lr;
; #pragma unroll
;                     for (int r = 0; r < 4; ++r) { const int i = 16 * mt + 4 * lq + r; const float v = ((i == jc) ? 1.f : 0.f) - (float)Mb[0][i * 72 + jc]; tacc[t][r] = v; TAb[0][i * 72 + jc] = (h16)v; } }
;     ...
;                 NEU_SQUARE(0, 1);
;                 __syncthreads();
.LBB0_1063:
	s_or_b64 exec, exec, s[4:5]
	v_ashrrev_i32_e32 v10, 7, v154
	v_lshlrev_b32_e32 v2, 1, v37
	v_lshlrev_b32_e32 v11, 4, v10
	v_and_b32_e32 v44, 2, v2
	v_or_b32_e32 v16, v38, v11
	v_lshl_or_b32 v37, v44, 4, v32
	v_mul_lo_u32 v6, v16, s82
	v_add_lshl_u32 v3, v6, v37, 1
	v_add_u32_e32 v4, s80, v3
	s_waitcnt lgkmcnt(0)
	s_barrier
	ds_read_u16 v4, v4
	v_cmp_eq_u32_e32 vcc, v16, v37
	v_readlane_b32 s6, v252, 11
	v_add_u32_e32 v8, 0x48, v6
	v_cndmask_b32_e64 v2, 0, 1.0, vcc
	s_waitcnt lgkmcnt(0)
	v_cvt_f32_f16_e32 v4, v4
	v_add_u32_e32 v3, s6, v3
	v_or_b32_e32 v7, 1, v16
	v_cmp_eq_u32_e32 vcc, v7, v37
	v_sub_f32_e32 v2, v2, v4
	v_cvt_f16_f32_e32 v4, v2
	v_add_u32_e32 v12, 0x90, v6
	v_or_b32_e32 v9, 2, v16
	v_add_u32_e32 v17, 0xd8, v6
	ds_write_b16 v3, v4
	v_add_lshl_u32 v4, v8, v37, 1
	v_add_u32_e32 v5, s80, v4
	ds_read_u16 v5, v5
	v_cndmask_b32_e64 v3, 0, 1.0, vcc
	v_add_u32_e32 v4, s6, v4
	v_cmp_eq_u32_e32 vcc, v9, v37
	v_add_lshl_u32 v19, v17, v37, 1
	s_waitcnt lgkmcnt(0)
	v_cvt_f32_f16_e32 v5, v5
	v_add_u32_e32 v20, s80, v19
	v_or_b32_e32 v50, 1, v44
	v_add_u32_e32 v19, s6, v19
	v_sub_f32_e32 v3, v3, v5
	v_cvt_f16_f32_e32 v5, v3
	v_lshl_or_b32 v41, v50, 4, v32
	v_add_lshl_u32 v8, v8, v41, 1
	v_or_b32_e32 v11, v11, v32
	ds_write_b16 v4, v5
	v_add_lshl_u32 v5, v12, v37, 1
	v_add_u32_e32 v13, s80, v5
	ds_read_u16 v13, v13
	v_cndmask_b32_e64 v4, 0, 1.0, vcc
	v_add_u32_e32 v5, s6, v5
	v_mul_lo_u32 v43, v11, s60
	v_lshlrev_b32_e32 v49, 1, v36
	s_waitcnt lgkmcnt(0)
	v_cvt_f32_f16_e32 v13, v13
	v_lshlrev_b32_e32 v57, 5, v10
	v_mul_lo_u32 v42, v16, s60
	v_lshlrev_b32_e32 v55, 1, v37
	v_sub_f32_e32 v4, v4, v13
	v_cvt_f16_f32_e32 v13, v4
	v_readlane_b32 s5, v252, 13
	v_add_u32_e32 v40, 0x90, v42
	v_add_u32_e32 v39, 0x120, v42
	ds_write_b16 v5, v13
	ds_read_u16 v20, v20
	v_or_b32_e32 v13, 3, v16
	v_cmp_eq_u32_e32 vcc, v13, v37
	v_readlane_b32 s4, v252, 12
	v_add_u32_e32 v38, 0x1b0, v42
	s_waitcnt lgkmcnt(0)
	v_cvt_f32_f16_e32 v20, v20
	v_cndmask_b32_e64 v5, 0, 1.0, vcc
	v_cmp_eq_u32_e32 vcc, v16, v41
	v_add3_u32 v45, s4, v57, v36
	v_sub_f32_e32 v5, v5, v20
	v_cvt_f16_f32_e32 v20, v5
	v_mad_u32_u24 v26, v37, s60, v45
	v_lshlrev_b32_e32 v54, 1, v41
	v_add_u32_e32 v48, s4, v49
	ds_write_b16 v19, v20
	v_add_lshl_u32 v20, v41, v6, 1
	v_add_u32_e32 v6, s80, v20
	ds_read_u16 v6, v6
	v_cndmask_b32_e64 v19, 0, 1.0, vcc
	v_add_u32_e32 v20, s6, v20
	v_cmp_eq_u32_e32 vcc, v7, v41
	v_readlane_b32 s4, v253, 62
	s_waitcnt lgkmcnt(0)
	v_cvt_f32_f16_e32 v6, v6
	v_cndmask_b32_e64 v7, 0, 1.0, vcc
	v_cmp_eq_u32_e32 vcc, v9, v41
	v_add_lshl_u32 v9, v12, v41, 1
	v_sub_f32_e32 v6, v19, v6
	v_cvt_f16_f32_e32 v19, v6
	v_add_u32_e32 v12, s80, v9
	v_add_u32_e32 v9, s6, v9
	v_add_u32_e32 v51, s4, v0
	ds_write_b16 v20, v19
	v_add_u32_e32 v19, s80, v8
	ds_read_u16 v19, v19
	v_add_u32_e32 v8, s6, v8
	v_add3_u32 v56, s5, v43, v49
	v_add3_u32 v72, s14, v57, v36
	v_add_u32_e32 v36, s80, v55
	s_waitcnt lgkmcnt(0)
	v_cvt_f32_f16_e32 v19, v19
	v_add_u32_e32 v57, v36, v40
	s_mov_b32 s12, 64
	v_sub_f32_e32 v7, v7, v19
	v_cvt_f16_f32_e32 v19, v7
	ds_write_b16 v8, v19
	ds_read_u16 v12, v12
	v_cndmask_b32_e64 v8, 0, 1.0, vcc
	v_cmp_eq_u32_e32 vcc, v13, v41
	v_add_u32_e32 v19, s14, v49
	v_mad_u32_u24 v27, v37, s60, v19
	s_waitcnt lgkmcnt(0)
	v_cvt_f32_f16_e32 v12, v12
	v_sub_f32_e32 v8, v8, v12
	v_cvt_f16_f32_e32 v12, v8
	ds_write_b16 v9, v12
	v_add_lshl_u32 v12, v17, v41, 1
	v_add_u32_e32 v13, s80, v12
	ds_read_u16 v13, v13
	v_cndmask_b32_e64 v9, 0, 1.0, vcc
	v_add_u32_e32 v12, s6, v12
	v_add3_u32 v17, s80, v43, v49
	s_and_b64 vcc, exec, s[84:85]
	s_waitcnt lgkmcnt(0)
	v_cvt_f32_f16_e32 v13, v13
	v_sub_f32_e32 v9, v9, v13
	v_cvt_f16_f32_e32 v13, v9
	ds_write_b16 v12, v13
	ds_read_b128 v[10:13], v17
	ds_read_b128 v[20:23], v27
	s_waitcnt lgkmcnt(0)
	v_mfma_f32_16x16x32_f16 v[10:13], v[10:13], v[20:23], 0
	ds_read_b128 v[20:23], v17 offset:64
	ds_read_b128 v[28:31], v27 offset:64
	s_waitcnt lgkmcnt(0)
	v_mfma_f32_16x16x32_f16 v[10:13], v[20:23], v[28:31], v[10:13]
	v_add_u32_e32 v20, s5, v55
	v_add_u32_e32 v29, v20, v40
	v_add_u32_e32 v28, v20, v39
	s_nop 4
	v_cvt_f16_f32_e32 v16, v11
	v_cvt_f16_f32_e32 v21, v10
	v_add_u32_e32 v30, v20, v42
	v_add_u32_e32 v25, v20, v38
	ds_write_b16 v29, v16
	v_cvt_f16_f32_e32 v16, v12
	ds_write_b16 v30, v21
	v_mad_u32_u24 v22, v41, s60, v19
	v_mad_u32_u24 v31, v37, s60, v48
	ds_write_b16 v28, v16
	v_cvt_f16_f32_e32 v16, v13
	v_cvt_pk_f16_f32 v13, v12, v13
	v_cvt_pk_f16_f32 v12, v10, v11
	v_mad_u32_u24 v48, v41, s60, v48
	ds_write_b16 v25, v16
	ds_write_b64 v26, v[12:13]
	ds_read_b128 v[10:13], v17
	ds_read_b128 v[58:61], v22
	s_waitcnt lgkmcnt(0)
	v_mfma_f32_16x16x32_f16 v[10:13], v[10:13], v[58:61], 0
	ds_read_b128 v[58:61], v17 offset:64
	ds_read_b128 v[62:65], v22 offset:64
	v_add_u32_e32 v16, s5, v54
	v_add_u32_e32 v24, v16, v42
	s_waitcnt lgkmcnt(0)
	v_mfma_f32_16x16x32_f16 v[10:13], v[58:61], v[62:65], v[10:13]
	v_add_u32_e32 v23, v16, v40
	v_add_u32_e32 v21, v16, v39
	v_lshlrev_b32_e32 v62, 5, v44
	s_nop 4
	v_cvt_f16_f32_e32 v19, v10
	v_cvt_f16_f32_e32 v20, v13
	v_cvt_pk_f16_f32 v13, v12, v13
	v_lshlrev_b32_e32 v63, 5, v50
	ds_write_b16 v24, v19
	v_cvt_f16_f32_e32 v19, v11
	v_mad_u32_u24 v37, v37, s60, v72
	v_add_u32_e32 v54, s80, v54
	ds_write_b16 v23, v19
	v_cvt_f16_f32_e32 v19, v12
	v_cvt_pk_f16_f32 v12, v10, v11
	ds_write_b16 v21, v19
	v_add_u32_e32 v19, v16, v38
	ds_write_b16 v19, v20
	v_mad_u32_u24 v20, v41, s60, v45
	v_add3_u32 v16, s6, v43, v49
	ds_write_b64 v20, v[12:13]
	s_waitcnt lgkmcnt(0)
	s_barrier
; #define LAS __attribute__((address_space(3)))
; __device__ __forceinline__ f32x4 mma16(const h16x8 a, const h16x8 b, const f32x4 c) { return __builtin_amdgcn_mfma_f32_16x16x32_f16(a, b, c, 0, 0, 0); }
; __device__ __forceinline__ void phase_even_mix(const int wid_s, CParams& p, int j, LAS unsigned char* lds) {
;     ...
; #pragma unroll
;                 for (int st = 0; st < 5; ++st) {
;                     const int mc = (st + 1) & 1, tc = st & 1;
; #pragma unroll
;                     for (int t = 0; t < 2; ++t) {
; #pragma unroll
;                         for (int ks = 0; ks < 2; ++ks) tacc[t] = mma16(*(const LAS h16x8*)(TAb[tc] + (16 * mt + lr) * 72 + 32 * ks + 8 * lq), *(const LAS h16x8*)(MTb[mc] + (16 * (nt0 + t) + lr) * 72 + 32 * ks + 8 * lq), tacc[t]);
;                         const int jc = 16 * (nt0 + t) + lr;
; #pragma unroll
;                         for (int r = 0; r < 4; ++r) TAb[tc ^ 1][(16 * mt + 4 * lq + r) * 72 + jc] = (h16)tacc[t][r];
;                     }
;                     if (st < 4) NEU_SQUARE(mc, mc ^ 1);
;                     __syncthreads();
;                 }
	ds_read_b128 v[10:13], v16
	ds_read_b128 v[58:61], v31
	s_waitcnt lgkmcnt(0)
	v_mfma_f32_16x16x32_f16 v[2:5], v[10:13], v[58:61], v[2:5]
	ds_read_b128 v[10:13], v16 offset:64
	ds_read_b128 v[58:61], v31 offset:64
	v_mad_u32_u24 v41, v41, s60, v72
	v_add3_u32 v43, s4, v43, v49
	s_waitcnt lgkmcnt(0)
	v_mfma_f32_16x16x32_f16 v[10:13], v[10:13], v[58:61], v[2:5]
	v_add_u32_e32 v49, s6, v0
	s_nop 1
	v_add_u32_e32 v2, v51, v62
	v_add_u32_e32 v44, v2, v42
	s_nop 2
	v_cvt_f16_f32_e32 v3, v10
	v_add_u32_e32 v46, v2, v40
	v_add_u32_e32 v47, v2, v39
	v_add_u32_e32 v45, v2, v38
	ds_write_b16 v44, v3
	v_cvt_f16_f32_e32 v3, v11
	s_movk_i32 s6, 0x1a00
	ds_write_b16 v46, v3
	v_cvt_f16_f32_e32 v3, v12
	ds_write_b16 v47, v3
	v_cvt_f16_f32_e32 v3, v13
	ds_write_b16 v45, v3
	ds_read_b128 v[2:5], v16
	ds_read_b128 v[58:61], v48
	s_waitcnt lgkmcnt(0)
	v_mfma_f32_16x16x32_f16 v[2:5], v[2:5], v[58:61], v[6:9]
	s_nop 2
	ds_read_b128 v[6:9], v16 offset:64
	ds_read_b128 v[58:61], v48 offset:64
	s_waitcnt lgkmcnt(0)
	v_mfma_f32_16x16x32_f16 v[2:5], v[6:9], v[58:61], v[2:5]
	v_add_u32_e32 v6, v51, v63
	v_add_u32_e32 v50, v6, v42
	v_add_u32_e32 v51, v6, v40
	s_nop 4
	v_cvt_f16_f32_e32 v7, v2
	v_add_u32_e32 v52, v6, v39
	v_add_u32_e32 v53, v6, v38
	ds_write_b16 v50, v7
	v_cvt_f16_f32_e32 v7, v3
	ds_write_b16 v51, v7
	v_cvt_f16_f32_e32 v7, v4
	ds_write_b16 v52, v7
	v_cvt_f16_f32_e32 v7, v5
	ds_write_b16 v53, v7
	ds_read_b128 v[6:9], v56
	ds_read_b128 v[58:61], v31
	s_waitcnt lgkmcnt(0)
	v_mfma_f32_16x16x32_f16 v[6:9], v[6:9], v[58:61], 0
	ds_read_b128 v[58:61], v56 offset:64
	ds_read_b128 v[64:67], v31 offset:64
	s_waitcnt lgkmcnt(0)
	v_mfma_f32_16x16x32_f16 v[6:9], v[58:61], v[64:67], v[6:9]
	v_add_u32_e32 v58, v36, v42
	v_add_u32_e32 v61, v54, v42
	v_add_u32_e32 v60, v54, v40
	s_nop 4
	v_cvt_f16_f32_e32 v55, v6
	v_cvt_f16_f32_e32 v59, v8
	ds_write_b16 v58, v55
	v_cvt_f16_f32_e32 v55, v7
	ds_write_b16 v57, v55
	v_add_u32_e32 v55, v36, v39
	ds_write_b16 v55, v59
	v_cvt_f16_f32_e32 v59, v9
	v_cvt_pk_f16_f32 v9, v8, v9
	v_cvt_pk_f16_f32 v8, v6, v7
	v_add_u32_e32 v36, v36, v38
	ds_write_b16 v36, v59
	ds_write_b64 v37, v[8:9]
	ds_read_b128 v[6:9], v56
	ds_read_b128 v[64:67], v48
	s_waitcnt lgkmcnt(0)
	v_mfma_f32_16x16x32_f16 v[6:9], v[6:9], v[64:67], 0
	ds_read_b128 v[64:67], v56 offset:64
	ds_read_b128 v[68:71], v48 offset:64
	s_waitcnt lgkmcnt(0)
	v_mfma_f32_16x16x32_f16 v[6:9], v[64:67], v[68:71], v[6:9]
	s_nop 7
	v_cvt_f16_f32_e32 v59, v6
	v_cvt_f16_f32_e32 v64, v8
	ds_write_b16 v61, v59
	v_cvt_f16_f32_e32 v59, v7
	ds_write_b16 v60, v59
	v_add_u32_e32 v59, v54, v39
	ds_write_b16 v59, v64
	v_cvt_f16_f32_e32 v64, v9
	v_cvt_pk_f16_f32 v9, v8, v9
	v_cvt_pk_f16_f32 v8, v6, v7
	v_add_u32_e32 v54, v54, v38
	ds_write_b16 v54, v64
	ds_write_b64 v41, v[8:9]
	s_waitcnt lgkmcnt(0)
	s_barrier
	ds_read_b128 v[6:9], v43
	ds_read_b128 v[64:67], v27
	s_waitcnt lgkmcnt(0)
	v_mfma_f32_16x16x32_f16 v[6:9], v[6:9], v[64:67], v[10:13]
	s_nop 2
	ds_read_b128 v[10:13], v43 offset:64
	ds_read_b128 v[64:67], v27 offset:64
	s_waitcnt lgkmcnt(0)
	v_mfma_f32_16x16x32_f16 v[6:9], v[10:13], v[64:67], v[6:9]
	v_add_u32_e32 v11, v49, v62
	v_add_u32_e32 v10, v11, v42
	v_add_u32_e32 v49, v49, v63
	s_nop 4
	v_cvt_f16_f32_e32 v12, v6
	v_cvt_f16_f32_e32 v13, v7
	v_cvt_f16_f32_e32 v62, v8
	v_add_u32_e32 v42, v49, v42
	ds_write_b16 v10, v12
	v_add_u32_e32 v12, v11, v40
	ds_write_b16 v12, v13
	v_add_u32_e32 v13, v11, v39
	ds_write_b16 v13, v62
	v_cvt_f16_f32_e32 v62, v9
	v_add_u32_e32 v11, v11, v38
	v_add_u32_e32 v40, v49, v40
	v_add_u32_e32 v74, v49, v39
	ds_write_b16 v11, v62
	ds_read_b128 v[64:67], v43
	ds_read_b128 v[68:71], v22
	s_waitcnt lgkmcnt(0)
	v_mfma_f32_16x16x32_f16 v[2:5], v[64:67], v[68:71], v[2:5]
	ds_read_b128 v[64:67], v43 offset:64
	ds_read_b128 v[68:71], v22 offset:64
	v_add_u32_e32 v49, v49, v38
	s_waitcnt lgkmcnt(0)
	v_mfma_f32_16x16x32_f16 v[2:5], v[64:67], v[68:71], v[2:5]
	s_nop 7
	v_cvt_f16_f32_e32 v62, v2
	v_cvt_f16_f32_e32 v39, v5
	ds_write_b16 v42, v62
	v_cvt_f16_f32_e32 v62, v3
	ds_write_b16 v49, v39
	ds_write_b16 v40, v62
	v_cvt_f16_f32_e32 v62, v4
	ds_write_b16 v74, v62
	ds_read_b128 v[62:65], v17
	ds_read_b128 v[66:69], v27
	s_waitcnt lgkmcnt(0)
	v_mfma_f32_16x16x32_f16 v[62:65], v[62:65], v[66:69], 0
	ds_read_b128 v[66:69], v17 offset:64
	ds_read_b128 v[70:73], v27 offset:64
	s_waitcnt lgkmcnt(0)
	v_mfma_f32_16x16x32_f16 v[62:65], v[66:69], v[70:73], v[62:65]
	s_nop 7
	v_cvt_f16_f32_e32 v38, v62
	v_cvt_f16_f32_e32 v66, v65
	v_cvt_pk_f16_f32 v39, v64, v65
	ds_write_b16 v30, v38
	v_cvt_f16_f32_e32 v38, v63
	ds_write_b16 v29, v38
	v_cvt_f16_f32_e32 v38, v64
	ds_write_b16 v28, v38
	v_cvt_pk_f16_f32 v38, v62, v63
	ds_write_b16 v25, v66
	ds_write_b64 v26, v[38:39]
	ds_read_b128 v[62:65], v17
	ds_read_b128 v[66:69], v22
	s_waitcnt lgkmcnt(0)
	v_mfma_f32_16x16x32_f16 v[62:65], v[62:65], v[66:69], 0
	ds_read_b128 v[66:69], v17 offset:64
	ds_read_b128 v[70:73], v22 offset:64
	s_waitcnt lgkmcnt(0)
	v_mfma_f32_16x16x32_f16 v[62:65], v[66:69], v[70:73], v[62:65]
	s_nop 7
	v_cvt_f16_f32_e32 v38, v62
	v_cvt_f16_f32_e32 v66, v65
	v_cvt_pk_f16_f32 v39, v64, v65
	ds_write_b16 v24, v38
	v_cvt_f16_f32_e32 v38, v63
	ds_write_b16 v23, v38
	v_cvt_f16_f32_e32 v38, v64
	ds_write_b16 v21, v38
	v_cvt_pk_f16_f32 v38, v62, v63
	ds_write_b16 v19, v66
	ds_write_b64 v20, v[38:39]
	s_waitcnt lgkmcnt(0)
	s_barrier
; #define LAS __attribute__((address_space(3)))
; __device__ __forceinline__ f32x4 mma16(const h16x8 a, const h16x8 b, const f32x4 c) { return __builtin_amdgcn_mfma_f32_16x16x32_f16(a, b, c, 0, 0, 0); }
; __device__ __forceinline__ void phase_even_mix(const int wid_s, CParams& p, int j, LAS unsigned char* lds) {
;     ...
; #pragma unroll
;                 for (int st = 0; st < 5; ++st) {
;                     const int mc = (st + 1) & 1, tc = st & 1;
; #pragma unroll
;                     for (int t = 0; t < 2; ++t) {
; #pragma unroll
;                         for (int ks = 0; ks < 2; ++ks) tacc[t] = mma16(*(const LAS h16x8*)(TAb[tc] + (16 * mt + lr) * 72 + 32 * ks + 8 * lq), *(const LAS h16x8*)(MTb[mc] + (16 * (nt0 + t) + lr) * 72 + 32 * ks + 8 * lq), tacc[t]);
;                         const int jc = 16 * (nt0 + t) + lr;
; #pragma unroll
;                         for (int r = 0; r < 4; ++r) TAb[tc ^ 1][(16 * mt + 4 * lq + r) * 72 + jc] = (h16)tacc[t][r];
;                     }
;                     if (st < 4) NEU_SQUARE(mc, mc ^ 1);
;                     __syncthreads();
;                 }
	ds_read_b128 v[62:65], v16
	ds_read_b128 v[66:69], v31
	s_waitcnt lgkmcnt(0)
	v_mfma_f32_16x16x32_f16 v[6:9], v[62:65], v[66:69], v[6:9]
	ds_read_b128 v[62:65], v16 offset:64
	ds_read_b128 v[66:69], v31 offset:64
	s_waitcnt lgkmcnt(0)
	v_mfma_f32_16x16x32_f16 v[6:9], v[62:65], v[66:69], v[6:9]
	s_nop 7
	v_cvt_f16_f32_e32 v38, v6
	ds_write_b16 v44, v38
	v_cvt_f16_f32_e32 v38, v7
	ds_write_b16 v46, v38
	v_cvt_f16_f32_e32 v38, v8
	ds_write_b16 v47, v38
	v_cvt_f16_f32_e32 v38, v9
	ds_write_b16 v45, v38
	ds_read_b128 v[62:65], v16
	ds_read_b128 v[66:69], v48
	s_waitcnt lgkmcnt(0)
	v_mfma_f32_16x16x32_f16 v[2:5], v[62:65], v[66:69], v[2:5]
	ds_read_b128 v[62:65], v16 offset:64
	ds_read_b128 v[66:69], v48 offset:64
	s_waitcnt lgkmcnt(0)
	v_mfma_f32_16x16x32_f16 v[2:5], v[62:65], v[66:69], v[2:5]
	s_nop 7
	v_cvt_f16_f32_e32 v38, v2
	ds_write_b16 v50, v38
	v_cvt_f16_f32_e32 v38, v3
	ds_write_b16 v51, v38
	v_cvt_f16_f32_e32 v38, v4
	ds_write_b16 v52, v38
	v_cvt_f16_f32_e32 v38, v5
	ds_write_b16 v53, v38
	ds_read_b128 v[62:65], v56
	ds_read_b128 v[66:69], v31
	s_waitcnt lgkmcnt(0)
	v_mfma_f32_16x16x32_f16 v[62:65], v[62:65], v[66:69], 0
	ds_read_b128 v[66:69], v56 offset:64
	ds_read_b128 v[70:73], v31 offset:64
	s_waitcnt lgkmcnt(0)
	v_mfma_f32_16x16x32_f16 v[62:65], v[66:69], v[70:73], v[62:65]
	s_nop 7
	v_cvt_f16_f32_e32 v38, v62
	v_cvt_pk_f16_f32 v39, v64, v65
	ds_write_b16 v58, v38
	v_cvt_f16_f32_e32 v38, v63
	ds_write_b16 v57, v38
	v_cvt_f16_f32_e32 v38, v64
	ds_write_b16 v55, v38
	v_cvt_f16_f32_e32 v55, v65
	v_cvt_pk_f16_f32 v38, v62, v63
	ds_write_b16 v36, v55
	ds_write_b64 v37, v[38:39]
	ds_read_b128 v[36:39], v56
	ds_read_b128 v[62:65], v48
	s_waitcnt lgkmcnt(0)
	v_mfma_f32_16x16x32_f16 v[36:39], v[36:39], v[62:65], 0
	ds_read_b128 v[62:65], v56 offset:64
	ds_read_b128 v[66:69], v48 offset:64
	s_waitcnt lgkmcnt(0)
	v_mfma_f32_16x16x32_f16 v[36:39], v[62:65], v[66:69], v[36:39]
	s_nop 7
	v_cvt_f16_f32_e32 v55, v36
	ds_write_b16 v61, v55
	v_cvt_f16_f32_e32 v55, v37
	ds_write_b16 v60, v55
	v_cvt_f16_f32_e32 v55, v38
	ds_write_b16 v59, v55
	v_cvt_f16_f32_e32 v55, v39
	v_cvt_pk_f16_f32 v39, v38, v39
	v_cvt_pk_f16_f32 v38, v36, v37
	ds_write_b16 v54, v55
	ds_write_b64 v41, v[38:39]
	s_waitcnt lgkmcnt(0)
	s_barrier
	ds_read_b128 v[36:39], v43
	ds_read_b128 v[54:57], v27
	s_waitcnt lgkmcnt(0)
	v_mfma_f32_16x16x32_f16 v[6:9], v[36:39], v[54:57], v[6:9]
	ds_read_b128 v[36:39], v43 offset:64
	ds_read_b128 v[54:57], v27 offset:64
	s_waitcnt lgkmcnt(0)
	v_mfma_f32_16x16x32_f16 v[6:9], v[36:39], v[54:57], v[6:9]
	s_nop 7
	v_cvt_f16_f32_e32 v36, v6
	ds_write_b16 v10, v36
	v_cvt_f16_f32_e32 v10, v7
	ds_write_b16 v12, v10
	v_cvt_f16_f32_e32 v10, v8
	ds_write_b16 v13, v10
	v_cvt_f16_f32_e32 v10, v9
	ds_write_b16 v11, v10
	ds_read_b128 v[10:13], v43
	ds_read_b128 v[36:39], v22
	s_waitcnt lgkmcnt(0)
	v_mfma_f32_16x16x32_f16 v[2:5], v[10:13], v[36:39], v[2:5]
	ds_read_b128 v[10:13], v43 offset:64
	ds_read_b128 v[36:39], v22 offset:64
	s_waitcnt lgkmcnt(0)
	v_mfma_f32_16x16x32_f16 v[2:5], v[10:13], v[36:39], v[2:5]
	s_nop 7
	v_cvt_f16_f32_e32 v10, v2
	ds_write_b16 v42, v10
	v_cvt_f16_f32_e32 v10, v3
	ds_write_b16 v40, v10
	v_cvt_f16_f32_e32 v10, v4
	ds_write_b16 v74, v10
	v_cvt_f16_f32_e32 v10, v5
	ds_write_b16 v49, v10
	ds_read_b128 v[10:13], v17
	ds_read_b128 v[36:39], v27
	s_waitcnt lgkmcnt(0)
	v_mfma_f32_16x16x32_f16 v[10:13], v[10:13], v[36:39], 0
	ds_read_b128 v[36:39], v17 offset:64
	ds_read_b128 v[40:43], v27 offset:64
	s_waitcnt lgkmcnt(0)
	v_mfma_f32_16x16x32_f16 v[10:13], v[36:39], v[40:43], v[10:13]
	s_nop 7
	v_cvt_f16_f32_e32 v27, v10
	ds_write_b16 v30, v27
	v_cvt_f16_f32_e32 v27, v11
	ds_write_b16 v29, v27
	v_cvt_f16_f32_e32 v27, v12
	ds_write_b16 v28, v27
	v_cvt_f16_f32_e32 v27, v13
	v_cvt_pk_f16_f32 v13, v12, v13
	v_cvt_pk_f16_f32 v12, v10, v11
	ds_write_b16 v25, v27
	ds_write_b64 v26, v[12:13]
	ds_read_b128 v[10:13], v17
	ds_read_b128 v[26:29], v22
	s_waitcnt lgkmcnt(0)
	v_mfma_f32_16x16x32_f16 v[10:13], v[10:13], v[26:29], 0
	ds_read_b128 v[26:29], v17 offset:64
	ds_read_b128 v[36:39], v22 offset:64
	s_waitcnt lgkmcnt(0)
	v_mfma_f32_16x16x32_f16 v[10:13], v[26:29], v[36:39], v[10:13]
	v_add_u32_e32 v28, v15, v33
	v_or_b32_e32 v26, s64, v34
	s_nop 5
	v_cvt_f16_f32_e32 v17, v10
	ds_write_b16 v24, v17
	v_cvt_f16_f32_e32 v17, v11
	ds_write_b16 v23, v17
	v_cvt_f16_f32_e32 v17, v12
	ds_write_b16 v21, v17
	v_cvt_f16_f32_e32 v17, v13
	v_cvt_pk_f16_f32 v13, v12, v13
	v_cvt_pk_f16_f32 v12, v10, v11
	ds_write_b16 v19, v17
	ds_write_b64 v20, v[12:13]
	s_waitcnt lgkmcnt(0)
	s_barrier
; #define LAS __attribute__((address_space(3)))
; __device__ __forceinline__ f32x4 mma16(const h16x8 a, const h16x8 b, const f32x4 c) { return __builtin_amdgcn_mfma_f32_16x16x32_f16(a, b, c, 0, 0, 0); }
; __device__ __forceinline__ void phase_even_mix(const int wid_s, CParams& p, int j, LAS unsigned char* lds) {
;     ...
;                 for (int st = 0; st < 5; ++st) {
;                     const int mc = (st + 1) & 1, tc = st & 1;
; #pragma unroll
;                     for (int t = 0; t < 2; ++t) {
; #pragma unroll
;                         for (int ks = 0; ks < 2; ++ks) tacc[t] = mma16(*(const LAS h16x8*)(TAb[tc] + (16 * mt + lr) * 72 + 32 * ks + 8 * lq), *(const LAS h16x8*)(MTb[mc] + (16 * (nt0 + t) + lr) * 72 + 32 * ks + 8 * lq), tacc[t]);
;                         const int jc = 16 * (nt0 + t) + lr;
; #pragma unroll
;                         for (int r = 0; r < 4; ++r) TAb[tc ^ 1][(16 * mt + 4 * lq + r) * 72 + jc] = (h16)tacc[t][r];
;                     }
;                     if (st < 4) NEU_SQUARE(mc, mc ^ 1);
;                     __syncthreads();
;                 }
;     ...
;             }
;             {
;                 const int sel = wave >> 2, mt = wave & 3;
;                 const LAS h16* Bm = sel ? KBGt : VBt;
;                 h16x8 af[2];
; #pragma unroll
;                 for (int ks = 0; ks < 2; ++ks) af[ks] = *(const LAS h16x8*)(T16 + (16 * mt + lr) * 72 + 32 * ks + 8 * lq);
; #pragma unroll
;                 for (int nt = 0; nt < 8; ++nt) {
;                     f32x4 acc = {0.f, 0.f, 0.f, 0.f};
; #pragma unroll
;                     for (int ks = 0; ks < 2; ++ks) acc = mma16(af[ks], *(const LAS h16x8*)(Bm + (16 * nt + lr) * 72 + 32 * ks + 8 * lq), acc);
; #pragma unroll
;                     for (int r = 0; r < 4; ++r) { const int i = 16 * mt + 4 * lq + r, d = 16 * nt + lr;
;                         proj[(size_t)(tc0 + i) * EV_N + (sel ? 0 : 512) + h * 128 + d] = (h16)acc[r]; }
;                 }
;             }
	ds_read_b128 v[10:13], v16
	ds_read_b128 v[20:23], v31
	s_waitcnt lgkmcnt(0)
	v_mfma_f32_16x16x32_f16 v[6:9], v[10:13], v[20:23], v[6:9]
	ds_read_b128 v[10:13], v16 offset:64
	ds_read_b128 v[20:23], v31 offset:64
	v_mad_u32_u24 v19, v32, s60, v28
	s_waitcnt lgkmcnt(0)
	v_mfma_f32_16x16x32_f16 v[6:9], v[10:13], v[20:23], v[6:9]
	s_nop 7
	v_cvt_f16_f32_e32 v6, v6
	ds_write_b16 v44, v6
	v_cvt_f16_f32_e32 v6, v7
	ds_write_b16 v46, v6
	v_cvt_f16_f32_e32 v6, v8
	ds_write_b16 v47, v6
	v_cvt_f16_f32_e32 v6, v9
	ds_write_b16 v45, v6
	ds_read_b128 v[6:9], v16
	ds_read_b128 v[10:13], v48
	s_waitcnt lgkmcnt(0)
	v_mfma_f32_16x16x32_f16 v[2:5], v[6:9], v[10:13], v[2:5]
	ds_read_b128 v[6:9], v16 offset:64
	ds_read_b128 v[10:13], v48 offset:64
	s_waitcnt lgkmcnt(0)
	v_mfma_f32_16x16x32_f16 v[2:5], v[6:9], v[10:13], v[2:5]
	v_lshlrev_b32_e32 v10, 1, v14
	v_mov_b32_e32 v11, v1
	s_nop 5
	v_cvt_f16_f32_e32 v2, v2
	ds_write_b16 v50, v2
	v_cvt_f16_f32_e32 v2, v3
	ds_write_b16 v51, v2
	v_cvt_f16_f32_e32 v2, v4
	ds_write_b16 v52, v2
	v_cvt_f16_f32_e32 v2, v5
	ds_write_b16 v53, v2
	v_mul_u32_u24_e32 v2, 0x90, v35
	v_add3_u32 v2, s4, v2, v33
	v_readlane_b32 s4, v252, 44
	v_readlane_b32 s5, v252, 45
	s_waitcnt lgkmcnt(0)
	s_barrier
	ds_read_b128 v[6:9], v2
	ds_read_b128 v[2:5], v2 offset:64
	v_lshl_add_u64 v[24:25], s[4:5], 0, v[10:11]
	ds_read_b128 v[10:13], v19
	ds_read_b128 v[14:17], v19 offset:64
	v_mbcnt_lo_u32_b32 v131, -1, 0
	v_mbcnt_hi_u32_b32 v131, -1, v131
	v_and_b32_e32 v132, 15, v131
	v_lshrrev_b32_e32 v131, 4, v131
	v_lshlrev_b32_e32 v131, 2, v131
	v_sub_u32_e32 v131, v132, v131
	v_add_u32_e32 v133, v26, v131
	v_lshlrev_b32_e32 v131, 1, v131
	v_sub_u32_e32 v134, 0, v131
	v_ashrrev_i32_e32 v135, 31, v134
	v_lshl_add_u64 v[134:135], v[24:25], 0, v[134:135]
	v_lshl_add_u64 v[134:135], v[134:135], 0, v[0:1]
	v_mad_i64_i32 v[134:135], s[4:5], v133, s6, v[134:135]
	ds_read_b128 v[20:23], v19 offset:2304
	ds_read_b128 v[24:27], v19 offset:2368
	s_waitcnt lgkmcnt(2)
	v_mfma_f32_16x16x32_f16 v[136:139], v[10:13], v[6:9], 0
	v_mfma_f32_16x16x32_f16 v[136:139], v[14:17], v[2:5], v[136:139]
	ds_read_b128 v[10:13], v19 offset:4608
	ds_read_b128 v[14:17], v19 offset:4672
	s_nop 7
	v_cvt_pk_f16_f32 v140, v136, v137
	v_cvt_pk_f16_f32 v141, v138, v139
	global_store_dwordx2 v[134:135], v[140:141], off
	s_waitcnt lgkmcnt(2)
	v_mfma_f32_16x16x32_f16 v[136:139], v[20:23], v[6:9], 0
	v_mfma_f32_16x16x32_f16 v[136:139], v[24:27], v[2:5], v[136:139]
	v_add_u32_e32 v142, v28, v18
	ds_read_b128 v[20:23], v142
	ds_read_b128 v[24:27], v142 offset:64
	s_nop 7
	v_cvt_pk_f16_f32 v140, v136, v137
	v_cvt_pk_f16_f32 v141, v138, v139
	global_store_dwordx2 v[134:135], v[140:141], off offset:32
	s_waitcnt lgkmcnt(2)
	v_mfma_f32_16x16x32_f16 v[136:139], v[10:13], v[6:9], 0
	v_mfma_f32_16x16x32_f16 v[136:139], v[14:17], v[2:5], v[136:139]
	ds_read_b128 v[10:13], v19 offset:9216
	ds_read_b128 v[14:17], v19 offset:9280
	s_nop 7
	v_cvt_pk_f16_f32 v140, v136, v137
	v_cvt_pk_f16_f32 v141, v138, v139
	global_store_dwordx2 v[134:135], v[140:141], off offset:64
	s_waitcnt lgkmcnt(2)
	v_mfma_f32_16x16x32_f16 v[136:139], v[20:23], v[6:9], 0
	v_mfma_f32_16x16x32_f16 v[136:139], v[24:27], v[2:5], v[136:139]
	ds_read_b128 v[20:23], v19 offset:11520
	ds_read_b128 v[24:27], v19 offset:11584
	s_nop 7
	v_cvt_pk_f16_f32 v140, v136, v137
	v_cvt_pk_f16_f32 v141, v138, v139
	global_store_dwordx2 v[134:135], v[140:141], off offset:96
	s_waitcnt lgkmcnt(2)
	v_mfma_f32_16x16x32_f16 v[136:139], v[10:13], v[6:9], 0
	v_mfma_f32_16x16x32_f16 v[136:139], v[14:17], v[2:5], v[136:139]
	ds_read_b128 v[10:13], v19 offset:13824
	ds_read_b128 v[14:17], v19 offset:13888
	s_nop 7
	v_cvt_pk_f16_f32 v140, v136, v137
	v_cvt_pk_f16_f32 v141, v138, v139
	global_store_dwordx2 v[134:135], v[140:141], off offset:128
	s_waitcnt lgkmcnt(2)
	v_mfma_f32_16x16x32_f16 v[136:139], v[20:23], v[6:9], 0
	v_mfma_f32_16x16x32_f16 v[136:139], v[24:27], v[2:5], v[136:139]
	ds_read_b128 v[20:23], v19 offset:16128
	ds_read_b128 v[24:27], v19 offset:16192
	s_nop 7
	v_cvt_pk_f16_f32 v140, v136, v137
	v_cvt_pk_f16_f32 v141, v138, v139
	global_store_dwordx2 v[134:135], v[140:141], off offset:160
	s_waitcnt lgkmcnt(2)
	v_mfma_f32_16x16x32_f16 v[136:139], v[10:13], v[6:9], 0
	v_mfma_f32_16x16x32_f16 v[136:139], v[14:17], v[2:5], v[136:139]
	s_nop 7
	v_cvt_pk_f16_f32 v140, v136, v137
	v_cvt_pk_f16_f32 v141, v138, v139
	global_store_dwordx2 v[134:135], v[140:141], off offset:192
	s_waitcnt lgkmcnt(0)
	v_mfma_f32_16x16x32_f16 v[136:139], v[20:23], v[6:9], 0
	v_mfma_f32_16x16x32_f16 v[136:139], v[24:27], v[2:5], v[136:139]
	s_nop 7
	v_cvt_pk_f16_f32 v140, v136, v137
	v_cvt_pk_f16_f32 v141, v138, v139
	global_store_dwordx2 v[134:135], v[140:141], off offset:224
	s_mov_b64 s[4:5], 0
	s_waitcnt vmcnt(63) expcnt(7) lgkmcnt(15)
	s_barrier
	s_cbranch_vccnz .LBB0_997
